# attention: last P.V MFMA group deferred past the workgroup barrier so it covers the K-fragment read latency of the next QK^T block; lazy rescale and pa3-aliased values moved behind it; packed fma repl
# baseline (speedup 1.0000x reference)
.LBB0_390:
	s_and_b32 s5, s5, 0x3fffffc0
	s_lshl_b32 s5, s5, 2
	s_add_i32 s5, s5, 0
	s_add_i32 s7, s5, 0x14000
	s_ashr_i32 s5, s6, 31
	s_lshr_b32 s5, s5, 26
	s_add_i32 s5, s5, s6
	s_addk_i32 s5, 0xff
	v_lshlrev_b32_e32 v58, 3, v186
	v_and_b32_e32 v15, 0xc0, v15
	v_lshlrev_b32_e32 v59, 1, v186
	s_ashr_i32 s6, s5, 6
	v_and_or_b32 v15, v58, 24, v15
	v_and_b32_e32 v59, 32, v59
	v_and_b32_e32 v58, 0x100, v58
	s_cmp_lg_u32 0, -1
	v_or3_b32 v15, v15, v59, v58
	s_cselect_b32 s5, 0, 0
	v_add_u32_e32 v190, s5, v15
	v_max_f32_e32 v15, v19, v19
	v_max_f32_e32 v58, v18, v18
	v_max_f32_e32 v15, v58, v15
	v_max3_f32 v15, v15, v20, v21
	v_max3_f32 v15, v15, v22, v23
	v_max3_f32 v15, v15, v24, v25
	v_max3_f32 v15, v15, v26, v27
	v_max3_f32 v15, v15, v28, v29
	v_max3_f32 v15, v15, v30, v31
	v_max3_f32 v15, v15, v32, v33
	v_max3_f32 v15, v15, v34, v35
	v_max3_f32 v15, v15, v36, v37
	v_max3_f32 v15, v15, v38, v39
	v_max3_f32 v15, v15, v40, v41
	v_max3_f32 v15, v15, v42, v43
	v_max3_f32 v15, v15, v44, v45
	v_max3_f32 v15, v15, v46, v47
	v_max3_f32 v15, v15, v48, v49
	v_mov_b32_e32 v58, v15
	s_nop 1
	v_permlane32_swap_b32_e32 v15, v58
	v_max_f32_e32 v58, v58, v58
	v_max_f32_e32 v15, v15, v15
	v_max_f32_e32 v15, v15, v58
	v_add_f32_e32 v58, 0x7149f2ca, v15
	v_mul_f32_e32 v58, 0x3d93cd3a, v58
	v_max_f32_e32 v15, 0xf149f2ca, v15
	v_cmp_ge_f32_e32 vcc, s86, v58
	v_sub_f32_e32 v58, 0xf149f2ca, v15
	v_mul_f32_e32 v58, 0x3dd53b94, v58
	v_exp_f32_e32 v58, v58
	s_cmp_eq_u64 vcc, exec
	s_cselect_b64 vcc, -1, 0
	v_cndmask_b32_e32 v208, v15, v173, vcc
	v_cndmask_b32_e64 v191, v58, 1.0, vcc
	v_mul_f32_e32 v58, 0xbdd53b94, v208
	v_fmamk_f32 v15, v18, 0x3dd53b94, v58
	v_fmamk_f32 v18, v19, 0x3dd53b94, v58
	v_fmamk_f32 v19, v20, 0x3dd53b94, v58
	v_fmamk_f32 v20, v21, 0x3dd53b94, v58
	v_fmamk_f32 v21, v22, 0x3dd53b94, v58
	v_fmamk_f32 v22, v23, 0x3dd53b94, v58
	v_fmamk_f32 v23, v24, 0x3dd53b94, v58
	v_fmamk_f32 v24, v25, 0x3dd53b94, v58
	v_fmamk_f32 v25, v26, 0x3dd53b94, v58
	v_fmamk_f32 v26, v27, 0x3dd53b94, v58
	v_fmamk_f32 v27, v28, 0x3dd53b94, v58
	v_fmamk_f32 v28, v29, 0x3dd53b94, v58
	v_fmamk_f32 v29, v30, 0x3dd53b94, v58
	v_fmamk_f32 v30, v31, 0x3dd53b94, v58
	v_fmamk_f32 v31, v32, 0x3dd53b94, v58
	v_mov_b32_e32 v32, v58
	v_fmac_f32_e32 v32, 0x3dd53b94, v33
	v_exp_f32_e32 v224, v15
	v_exp_f32_e32 v226, v18
	v_exp_f32_e32 v222, v19
	v_exp_f32_e32 v225, v20
	v_exp_f32_e32 v220, v21
	v_exp_f32_e32 v223, v22
	v_exp_f32_e32 v219, v23
	v_exp_f32_e32 v221, v24
	v_exp_f32_e32 v216, v25
	v_exp_f32_e32 v218, v26
	v_exp_f32_e32 v214, v27
	v_exp_f32_e32 v217, v28
	v_exp_f32_e32 v212, v29
	v_exp_f32_e32 v215, v30
	v_exp_f32_e32 v211, v31
	v_exp_f32_e32 v213, v32
	s_waitcnt vmcnt(0)
	s_or_b32 s5, s4, 31
	v_pk_fma_f32 v[160:161], v[48:49], s[30:31], v[58:59] op_sel_hi:[1,0,0]
	v_pk_fma_f32 v[162:163], v[46:47], s[30:31], v[58:59] op_sel_hi:[1,0,0]
	v_pk_fma_f32 v[164:165], v[44:45], s[30:31], v[58:59] op_sel_hi:[1,0,0]
	v_pk_fma_f32 v[166:167], v[42:43], s[30:31], v[58:59] op_sel_hi:[1,0,0]
	v_pk_fma_f32 v[168:169], v[40:41], s[30:31], v[58:59] op_sel_hi:[1,0,0]
	v_pk_fma_f32 v[170:171], v[38:39], s[30:31], v[58:59] op_sel_hi:[1,0,0]
	v_pk_fma_f32 v[180:181], v[36:37], s[30:31], v[58:59] op_sel_hi:[1,0,0]
	v_pk_fma_f32 v[182:183], v[34:35], s[30:31], v[58:59] op_sel_hi:[1,0,0]
	v_add_u32_e32 v209, 0xe000, v202
	s_cmp_lt_i32 s8, 0
	v_add_u32_e32 v207, 0xe000, v196
	v_add_u32_e32 v205, 0xe000, v197
	v_add_u32_e32 v206, 0xe000, v199
	v_add_u32_e32 v204, 0xe000, v198
	v_cmp_gt_u32_e64 s[8:9], 32, v186
	v_lshl_add_u32 v192, v187, 2, s7
	v_lshl_add_u32 v189, v17, 2, s7
	s_waitcnt vmcnt(4)
	ds_write_b128 v200, v[6:9] offset:16384
	s_waitcnt vmcnt(2)
	ds_write_b128 v201, v[54:57] offset:16384
	ds_write_b128 v202, v[2:5] offset:57344
	s_waitcnt vmcnt(1)
	ds_write_b128 v209, v[10:13] offset:12288
	s_waitcnt vmcnt(0)
	ds_write_b128 v203, v[50:53] offset:57344
	s_waitcnt lgkmcnt(0)
	s_barrier
	s_cbranch_scc1 .LBB0_419
	v_mov_b32_e32 v15, v1
	s_add_i32 s7, s4, 0xbfffff45
	v_lshl_add_u64 v[176:177], s[48:49], 0, v[14:15]
	v_lshl_add_u64 v[178:179], s[50:51], 0, v[0:1]
	v_add_u32_e32 v0, s7, v187
	v_mov_b32_e32 v14, v1
	v_sub_u32_e32 v210, v0, v17
	v_mov_b32_e32 v0, v1
	v_mov_b32_e32 v2, v1
	v_mov_b32_e32 v3, v1
	v_mov_b32_e32 v4, v1
	v_mov_b32_e32 v5, v1
	v_mov_b32_e32 v6, v1
	v_mov_b32_e32 v7, v1
	v_mov_b32_e32 v8, v1
	v_mov_b32_e32 v9, v1
	v_mov_b32_e32 v10, v1
	v_mov_b32_e32 v11, v1
	v_mov_b32_e32 v12, v1
	v_mov_b32_e32 v13, v1
	v_mov_b64_e32 v[94:95], v[14:15]
	v_mov_b64_e32 v[78:79], v[14:15]
	v_mov_b64_e32 v[62:63], v[14:15]
	v_mov_b64_e32 v[46:47], v[14:15]
	v_mov_b32_e32 v194, 0
	s_mov_b32 s7, 1
	s_movk_i32 s54, 0x7f
	v_mov_b64_e32 v[92:93], v[12:13]
	v_mov_b64_e32 v[90:91], v[10:11]
	v_mov_b64_e32 v[88:89], v[8:9]
	v_mov_b64_e32 v[86:87], v[6:7]
	v_mov_b64_e32 v[84:85], v[4:5]
	v_mov_b64_e32 v[82:83], v[2:3]
	v_mov_b64_e32 v[80:81], v[0:1]
	v_mov_b64_e32 v[76:77], v[12:13]
	v_mov_b64_e32 v[74:75], v[10:11]
	v_mov_b64_e32 v[72:73], v[8:9]
	v_mov_b64_e32 v[70:71], v[6:7]
	v_mov_b64_e32 v[68:69], v[4:5]
	v_mov_b64_e32 v[66:67], v[2:3]
	v_mov_b64_e32 v[64:65], v[0:1]
	v_mov_b64_e32 v[60:61], v[12:13]
	v_mov_b64_e32 v[58:59], v[10:11]
	v_mov_b64_e32 v[56:57], v[8:9]
	v_mov_b64_e32 v[54:55], v[6:7]
	v_mov_b64_e32 v[52:53], v[4:5]
	v_mov_b64_e32 v[50:51], v[2:3]
	v_mov_b64_e32 v[48:49], v[0:1]
	v_mov_b64_e32 v[44:45], v[12:13]
	v_mov_b64_e32 v[42:43], v[10:11]
	v_mov_b64_e32 v[40:41], v[8:9]
	v_mov_b64_e32 v[38:39], v[6:7]
	v_mov_b64_e32 v[36:37], v[4:5]
	v_mov_b64_e32 v[34:35], v[2:3]
	v_mov_b64_e32 v[32:33], v[0:1]
.Lh1_first:
	s_sub_i32 s10, s54, 63
	s_cmp_le_i32 s10, s5
	s_cselect_b64 s[76:77], -1, 0
	s_cmp_gt_i32 s10, s5
	s_cbranch_scc1 .LBB0_396
	ds_read_b128 v[236:239], v196 offset:57344
	ds_read_b128 v[240:243], v207 offset:12288
	ds_read_b128 v[246:249], v197 offset:57344
	ds_read_b128 v[250:253], v205 offset:12288
	ds_read_b128 v[6:9], v195
	ds_read_b128 v[10:13], v195 offset:1024
	ds_read_b128 v[2:5], v195 offset:2048
	v_cvt_pk_bf16_f32 v18, v224, v226
	v_cvt_pk_bf16_f32 v19, v222, v225
	v_cvt_pk_bf16_f32 v20, v220, v223
	v_cvt_pk_bf16_f32 v21, v219, v221
	v_cvt_pk_bf16_f32 v22, v216, v218
	v_cvt_pk_bf16_f32 v23, v214, v217
	v_cvt_pk_bf16_f32 v24, v212, v215
	v_cvt_pk_bf16_f32 v25, v211, v213
	v_add_f32_e32 v0, 0, v224
	v_add_f32_e32 v0, v226, v0
	v_add_f32_e32 v0, v222, v0
	v_add_f32_e32 v0, v225, v0
	v_add_f32_e32 v0, v220, v0
	v_add_f32_e32 v0, v223, v0
	v_add_f32_e32 v0, v219, v0
	v_add_f32_e32 v0, v221, v0
	s_waitcnt lgkmcnt(6)
	v_mfma_f32_32x32x16_bf16 v[112:127], v[236:239], v[156:159], 0
	ds_read_b128 v[236:239], v199 offset:57344
	v_add_f32_e32 v0, v216, v0
	v_add_f32_e32 v0, v218, v0
	v_permlane32_swap_b32_e32 v18, v20
	s_waitcnt lgkmcnt(6)
	v_mfma_f32_32x32x16_bf16 v[96:111], v[240:243], v[156:159], 0
	ds_read_b128 v[240:243], v206 offset:12288
	v_add_f32_e32 v0, v214, v0
	v_add_f32_e32 v0, v217, v0
	v_permlane32_swap_b32_e32 v19, v21
	s_waitcnt lgkmcnt(6)
	v_mfma_f32_32x32x16_bf16 v[112:127], v[246:249], v[152:155], v[112:127]
	ds_read_b128 v[246:249], v198 offset:57344
	v_add_f32_e32 v0, v212, v0
	v_add_f32_e32 v0, v215, v0
	s_waitcnt lgkmcnt(6)
	v_mfma_f32_32x32x16_bf16 v[96:111], v[250:253], v[152:155], v[96:111]
	ds_read_b128 v[250:253], v204 offset:12288
	v_permlane32_swap_b32_e32 v22, v24
	v_add_f32_e32 v0, v211, v0
	s_waitcnt lgkmcnt(3)
	v_mfma_f32_32x32x16_bf16 v[112:127], v[236:239], v[148:151], v[112:127]
	ds_read_b128 v[236:239], v196 offset:57472
	v_add_f32_e32 v0, v213, v0
	v_permlane32_swap_b32_e32 v23, v25
	s_waitcnt lgkmcnt(3)
	v_mfma_f32_32x32x16_bf16 v[96:111], v[240:243], v[148:151], v[96:111]
	ds_read_b128 v[240:243], v207 offset:12416
	v_exp_f32_e32 v182, v182
	v_exp_f32_e32 v183, v183
	s_waitcnt lgkmcnt(3)
	v_mfma_f32_32x32x16_bf16 v[112:127], v[246:249], v[144:147], v[112:127]
	ds_read_b128 v[246:249], v197 offset:57472
	v_exp_f32_e32 v180, v180
	v_exp_f32_e32 v181, v181
	s_waitcnt lgkmcnt(3)
	v_mfma_f32_32x32x16_bf16 v[96:111], v[250:253], v[144:147], v[96:111]
	ds_read_b128 v[250:253], v205 offset:12416
	v_add_f32_e32 v0, v182, v0
	v_exp_f32_e32 v170, v170
	s_waitcnt lgkmcnt(3)
	v_mfma_f32_32x32x16_bf16 v[112:127], v[236:239], v[140:143], v[112:127]
	ds_read_b128 v[236:239], v199 offset:57472
	v_add_f32_e32 v0, v183, v0
	v_exp_f32_e32 v171, v171
	s_waitcnt lgkmcnt(3)
	v_mfma_f32_32x32x16_bf16 v[96:111], v[240:243], v[140:143], v[96:111]
	ds_read_b128 v[240:243], v206 offset:12416
	v_add_f32_e32 v0, v180, v0
	v_exp_f32_e32 v168, v168
	s_waitcnt lgkmcnt(3)
	v_mfma_f32_32x32x16_bf16 v[112:127], v[246:249], v[136:139], v[112:127]
	ds_read_b128 v[246:249], v198 offset:57472
	v_add_f32_e32 v0, v181, v0
	v_exp_f32_e32 v169, v169
	s_waitcnt lgkmcnt(3)
	v_mfma_f32_32x32x16_bf16 v[96:111], v[250:253], v[136:139], v[96:111]
	ds_read_b128 v[250:253], v204 offset:12416
	v_cvt_pk_bf16_f32 v26, v182, v183
	v_cvt_pk_bf16_f32 v27, v180, v181
	s_waitcnt lgkmcnt(3)
	v_mfma_f32_32x32x16_bf16 v[112:127], v[236:239], v[132:135], v[112:127]
	ds_read_b128 v[236:239], v196 offset:57600
	v_add_f32_e32 v0, v170, v0
	v_exp_f32_e32 v166, v166
	s_waitcnt lgkmcnt(3)
	v_mfma_f32_32x32x16_bf16 v[96:111], v[240:243], v[132:135], v[96:111]
	ds_read_b128 v[240:243], v207 offset:12544
	v_add_f32_e32 v0, v171, v0
	v_exp_f32_e32 v167, v167
	s_waitcnt lgkmcnt(3)
	v_mfma_f32_32x32x16_bf16 v[112:127], v[246:249], v[128:131], v[112:127]
	ds_read_b128 v[246:249], v197 offset:57600
	v_add_f32_e32 v0, v168, v0
	v_exp_f32_e32 v164, v164
	s_waitcnt lgkmcnt(3)
	v_mfma_f32_32x32x16_bf16 v[96:111], v[250:253], v[128:131], v[96:111]
	ds_read_b128 v[250:253], v205 offset:12544
	v_add_f32_e32 v0, v169, v0
	v_exp_f32_e32 v165, v165
	s_waitcnt lgkmcnt(3)
	v_mfma_f32_32x32x16_bf16 v[112:127], v[236:239], v[6:9], v[112:127]
	ds_read_b128 v[236:239], v199 offset:57600
	v_cvt_pk_bf16_f32 v28, v170, v171
	v_cvt_pk_bf16_f32 v29, v168, v169
	s_waitcnt lgkmcnt(3)
	v_mfma_f32_32x32x16_bf16 v[96:111], v[240:243], v[6:9], v[96:111]
	ds_read_b128 v[240:243], v206 offset:12544
	ds_read_b128 v[6:9], v195 offset:3072
	v_add_f32_e32 v0, v166, v0
	v_exp_f32_e32 v162, v162
	s_waitcnt lgkmcnt(4)
	v_mfma_f32_32x32x16_bf16 v[112:127], v[246:249], v[10:13], v[112:127]
	ds_read_b128 v[246:249], v198 offset:57600
	v_permlane32_swap_b32_e32 v26, v28
	v_permlane32_swap_b32_e32 v27, v29
	s_waitcnt lgkmcnt(4)
	v_mfma_f32_32x32x16_bf16 v[96:111], v[250:253], v[10:13], v[96:111]
	ds_read_b128 v[250:253], v204 offset:12544
	v_add_f32_e32 v0, v167, v0
	v_exp_f32_e32 v163, v163
	s_waitcnt lgkmcnt(4)
	v_mfma_f32_32x32x16_bf16 v[112:127], v[236:239], v[2:5], v[112:127]
	v_add_f32_e32 v0, v164, v0
	v_exp_f32_e32 v160, v160
	s_waitcnt lgkmcnt(3)
	v_mfma_f32_32x32x16_bf16 v[96:111], v[240:243], v[2:5], v[96:111]
	v_add_f32_e32 v0, v165, v0
	v_exp_f32_e32 v161, v161
	s_waitcnt lgkmcnt(1)
	v_mfma_f32_32x32x16_bf16 v[112:127], v[246:249], v[6:9], v[112:127]
	v_cvt_pk_bf16_f32 v168, v166, v167
	v_cvt_pk_bf16_f32 v169, v164, v165
	s_waitcnt lgkmcnt(0)
	v_mfma_f32_32x32x16_bf16 v[96:111], v[250:253], v[6:9], v[96:111]
	v_add_f32_e32 v0, v162, v0
	v_add_f32_e32 v0, v163, v0
	v_add_f32_e32 v0, v160, v0
	v_add_f32_e32 v0, v161, v0
	v_cvt_pk_bf16_f32 v170, v162, v163
	v_cvt_pk_bf16_f32 v171, v160, v161
	v_mov_b32_e32 v14, v0
	s_nop 1
	v_permlane32_swap_b32_e32 v168, v170
	v_permlane32_swap_b32_e32 v169, v171
	v_permlane32_swap_b32_e32 v0, v14
	s_branch .Lattn_h1_join
.LBB0_394:
	s_sub_i32 s10, s54, 63
	s_cmp_le_i32 s10, s5
	s_cselect_b64 s[76:77], -1, 0
	s_cmp_gt_i32 s10, s5
	s_cbranch_scc1 .Lh1_skip_g3
	v_mfma_f32_32x32x16_bf16 v[32:47], v[18:21], v[236:239], v[32:47]
	ds_read_b128 v[236:239], v196 offset:57344
	v_mfma_f32_32x32x16_bf16 v[32:47], v[22:25], v[240:243], v[32:47]
	ds_read_b128 v[240:243], v207 offset:12288
	v_mfma_f32_32x32x16_bf16 v[32:47], v[26:29], v[246:249], v[32:47]
	ds_read_b128 v[246:249], v197 offset:57344
	v_mfma_f32_32x32x16_bf16 v[32:47], v[168:171], v[250:253], v[32:47]
	ds_read_b128 v[250:253], v205 offset:12288
	ds_read_b128 v[6:9], v195
	ds_read_b128 v[10:13], v195 offset:1024
	ds_read_b128 v[2:5], v195 offset:2048
	v_cmp_gt_f32_e32 vcc, 1.0, v235
	s_cbranch_vccz .Lqh1_norsc
	s_and_saveexec_b64 s[78:79], s[8:9]
	ds_write_b32 v192, v235 offset:128
	s_or_b64 exec, exec, s[78:79]
	s_waitcnt lgkmcnt(0)
	ds_read_b128 v[18:21], v189 offset:224
	ds_read_b128 v[22:25], v189 offset:192
	ds_read_b128 v[26:29], v189 offset:160
	ds_read_b128 v[168:171], v189 offset:128
	s_waitcnt lgkmcnt(3)
	v_pk_mul_f32 v[94:95], v[94:95], v[20:21]
	s_waitcnt lgkmcnt(2)
	v_pk_mul_f32 v[90:91], v[90:91], v[24:25]
	s_waitcnt lgkmcnt(1)
	v_pk_mul_f32 v[86:87], v[86:87], v[28:29]
	s_waitcnt lgkmcnt(0)
	v_pk_mul_f32 v[82:83], v[82:83], v[170:171]
	v_pk_mul_f32 v[92:93], v[92:93], v[18:19]
	v_pk_mul_f32 v[88:89], v[88:89], v[22:23]
	v_pk_mul_f32 v[84:85], v[84:85], v[26:27]
	v_pk_mul_f32 v[80:81], v[80:81], v[168:169]
	v_pk_mul_f32 v[78:79], v[78:79], v[20:21]
	v_pk_mul_f32 v[74:75], v[74:75], v[24:25]
	v_pk_mul_f32 v[70:71], v[70:71], v[28:29]
	v_pk_mul_f32 v[66:67], v[66:67], v[170:171]
	v_pk_mul_f32 v[76:77], v[76:77], v[18:19]
	v_pk_mul_f32 v[72:73], v[72:73], v[22:23]
	v_pk_mul_f32 v[68:69], v[68:69], v[26:27]
	v_pk_mul_f32 v[64:65], v[64:65], v[168:169]
	v_pk_mul_f32 v[62:63], v[62:63], v[20:21]
	v_pk_mul_f32 v[58:59], v[58:59], v[24:25]
	v_pk_mul_f32 v[54:55], v[54:55], v[28:29]
	v_pk_mul_f32 v[50:51], v[50:51], v[170:171]
	v_pk_mul_f32 v[60:61], v[60:61], v[18:19]
	v_pk_mul_f32 v[56:57], v[56:57], v[22:23]
	v_pk_mul_f32 v[52:53], v[52:53], v[26:27]
	v_pk_mul_f32 v[48:49], v[48:49], v[168:169]
	v_pk_mul_f32 v[46:47], v[46:47], v[20:21]
	v_pk_mul_f32 v[42:43], v[42:43], v[24:25]
	v_pk_mul_f32 v[38:39], v[38:39], v[28:29]
	v_pk_mul_f32 v[34:35], v[34:35], v[170:171]
	v_pk_mul_f32 v[44:45], v[44:45], v[18:19]
	v_pk_mul_f32 v[40:41], v[40:41], v[22:23]
	v_pk_mul_f32 v[36:37], v[36:37], v[26:27]
	v_pk_mul_f32 v[32:33], v[32:33], v[168:169]
.Lqh1_norsc:
	v_fmamk_f32 v168, v102, 0x3dd53b94, v254
	v_fmamk_f32 v169, v103, 0x3dd53b94, v254
	v_fmamk_f32 v170, v100, 0x3dd53b94, v254
	v_fmamk_f32 v171, v101, 0x3dd53b94, v254
	v_cvt_pk_bf16_f32 v18, v224, v226
	v_cvt_pk_bf16_f32 v19, v222, v225
	v_cvt_pk_bf16_f32 v20, v220, v223
	v_cvt_pk_bf16_f32 v21, v219, v221
	v_cvt_pk_bf16_f32 v22, v216, v218
	v_cvt_pk_bf16_f32 v23, v214, v217
	v_cvt_pk_bf16_f32 v24, v212, v215
	v_cvt_pk_bf16_f32 v25, v211, v213
	v_add_f32_e32 v0, 0, v224
	v_add_f32_e32 v0, v226, v0
	v_add_f32_e32 v0, v222, v0
	v_add_f32_e32 v0, v225, v0
	v_add_f32_e32 v0, v220, v0
	v_add_f32_e32 v0, v223, v0
	v_add_f32_e32 v0, v219, v0
	v_add_f32_e32 v0, v221, v0
	s_waitcnt lgkmcnt(6)
	v_mfma_f32_32x32x16_bf16 v[112:127], v[236:239], v[156:159], 0
	ds_read_b128 v[236:239], v199 offset:57344
	v_add_f32_e32 v0, v216, v0
	v_add_f32_e32 v0, v218, v0
	v_permlane32_swap_b32_e32 v18, v20
	s_waitcnt lgkmcnt(6)
	v_mfma_f32_32x32x16_bf16 v[96:111], v[240:243], v[156:159], 0
	ds_read_b128 v[240:243], v206 offset:12288
	v_add_f32_e32 v0, v214, v0
	v_add_f32_e32 v0, v217, v0
	v_permlane32_swap_b32_e32 v19, v21
	s_waitcnt lgkmcnt(6)
	v_mfma_f32_32x32x16_bf16 v[112:127], v[246:249], v[152:155], v[112:127]
	ds_read_b128 v[246:249], v198 offset:57344
	v_add_f32_e32 v0, v212, v0
	v_add_f32_e32 v0, v215, v0
	s_waitcnt lgkmcnt(6)
	v_mfma_f32_32x32x16_bf16 v[96:111], v[250:253], v[152:155], v[96:111]
	ds_read_b128 v[250:253], v204 offset:12288
	v_permlane32_swap_b32_e32 v22, v24
	v_add_f32_e32 v0, v211, v0
	s_waitcnt lgkmcnt(3)
	v_mfma_f32_32x32x16_bf16 v[112:127], v[236:239], v[148:151], v[112:127]
	ds_read_b128 v[236:239], v196 offset:57472
	v_add_f32_e32 v0, v213, v0
	v_permlane32_swap_b32_e32 v23, v25
	s_waitcnt lgkmcnt(3)
	v_mfma_f32_32x32x16_bf16 v[96:111], v[240:243], v[148:151], v[96:111]
	ds_read_b128 v[240:243], v207 offset:12416
	v_exp_f32_e32 v182, v182
	v_exp_f32_e32 v183, v183
	s_waitcnt lgkmcnt(3)
	v_mfma_f32_32x32x16_bf16 v[112:127], v[246:249], v[144:147], v[112:127]
	ds_read_b128 v[246:249], v197 offset:57472
	v_exp_f32_e32 v180, v180
	v_exp_f32_e32 v181, v181
	s_waitcnt lgkmcnt(3)
	v_mfma_f32_32x32x16_bf16 v[96:111], v[250:253], v[144:147], v[96:111]
	ds_read_b128 v[250:253], v205 offset:12416
	v_add_f32_e32 v0, v182, v0
	v_exp_f32_e32 v170, v170
	s_waitcnt lgkmcnt(3)
	v_mfma_f32_32x32x16_bf16 v[112:127], v[236:239], v[140:143], v[112:127]
	ds_read_b128 v[236:239], v199 offset:57472
	v_add_f32_e32 v0, v183, v0
	v_exp_f32_e32 v171, v171
	s_waitcnt lgkmcnt(3)
	v_mfma_f32_32x32x16_bf16 v[96:111], v[240:243], v[140:143], v[96:111]
	ds_read_b128 v[240:243], v206 offset:12416
	v_add_f32_e32 v0, v180, v0
	v_exp_f32_e32 v168, v168
	s_waitcnt lgkmcnt(3)
	v_mfma_f32_32x32x16_bf16 v[112:127], v[246:249], v[136:139], v[112:127]
	ds_read_b128 v[246:249], v198 offset:57472
	v_add_f32_e32 v0, v181, v0
	v_exp_f32_e32 v169, v169
	s_waitcnt lgkmcnt(3)
	v_mfma_f32_32x32x16_bf16 v[96:111], v[250:253], v[136:139], v[96:111]
	ds_read_b128 v[250:253], v204 offset:12416
	v_cvt_pk_bf16_f32 v26, v182, v183
	v_cvt_pk_bf16_f32 v27, v180, v181
	s_waitcnt lgkmcnt(3)
	v_mfma_f32_32x32x16_bf16 v[112:127], v[236:239], v[132:135], v[112:127]
	ds_read_b128 v[236:239], v196 offset:57600
	v_add_f32_e32 v0, v170, v0
	v_exp_f32_e32 v166, v166
	s_waitcnt lgkmcnt(3)
	v_mfma_f32_32x32x16_bf16 v[96:111], v[240:243], v[132:135], v[96:111]
	ds_read_b128 v[240:243], v207 offset:12544
	v_add_f32_e32 v0, v171, v0
	v_exp_f32_e32 v167, v167
	s_waitcnt lgkmcnt(3)
	v_mfma_f32_32x32x16_bf16 v[112:127], v[246:249], v[128:131], v[112:127]
	ds_read_b128 v[246:249], v197 offset:57600
	v_add_f32_e32 v0, v168, v0
	v_exp_f32_e32 v164, v164
	s_waitcnt lgkmcnt(3)
	v_mfma_f32_32x32x16_bf16 v[96:111], v[250:253], v[128:131], v[96:111]
	ds_read_b128 v[250:253], v205 offset:12544
	v_add_f32_e32 v0, v169, v0
	v_exp_f32_e32 v165, v165
	s_waitcnt lgkmcnt(3)
	v_mfma_f32_32x32x16_bf16 v[112:127], v[236:239], v[6:9], v[112:127]
	ds_read_b128 v[236:239], v199 offset:57600
	v_cvt_pk_bf16_f32 v28, v170, v171
	v_cvt_pk_bf16_f32 v29, v168, v169
	s_waitcnt lgkmcnt(3)
	v_mfma_f32_32x32x16_bf16 v[96:111], v[240:243], v[6:9], v[96:111]
	ds_read_b128 v[240:243], v206 offset:12544
	ds_read_b128 v[6:9], v195 offset:3072
	v_add_f32_e32 v0, v166, v0
	v_exp_f32_e32 v162, v162
	s_waitcnt lgkmcnt(4)
	v_mfma_f32_32x32x16_bf16 v[112:127], v[246:249], v[10:13], v[112:127]
	ds_read_b128 v[246:249], v198 offset:57600
	v_permlane32_swap_b32_e32 v26, v28
	v_permlane32_swap_b32_e32 v27, v29
	s_waitcnt lgkmcnt(4)
	v_mfma_f32_32x32x16_bf16 v[96:111], v[250:253], v[10:13], v[96:111]
	ds_read_b128 v[250:253], v204 offset:12544
	v_add_f32_e32 v0, v167, v0
	v_exp_f32_e32 v163, v163
	s_waitcnt lgkmcnt(4)
	v_mfma_f32_32x32x16_bf16 v[112:127], v[236:239], v[2:5], v[112:127]
	v_add_f32_e32 v0, v164, v0
	v_exp_f32_e32 v160, v160
	s_waitcnt lgkmcnt(3)
	v_mfma_f32_32x32x16_bf16 v[96:111], v[240:243], v[2:5], v[96:111]
	v_add_f32_e32 v0, v165, v0
	v_exp_f32_e32 v161, v161
	s_waitcnt lgkmcnt(1)
	v_mfma_f32_32x32x16_bf16 v[112:127], v[246:249], v[6:9], v[112:127]
	v_cvt_pk_bf16_f32 v168, v166, v167
	v_cvt_pk_bf16_f32 v169, v164, v165
	s_waitcnt lgkmcnt(0)
	v_mfma_f32_32x32x16_bf16 v[96:111], v[250:253], v[6:9], v[96:111]
	v_add_f32_e32 v0, v162, v0
	v_add_f32_e32 v0, v163, v0
	v_add_f32_e32 v0, v160, v0
	v_add_f32_e32 v0, v161, v0
	v_cvt_pk_bf16_f32 v170, v162, v163
	v_cvt_pk_bf16_f32 v171, v160, v161
	v_mov_b32_e32 v14, v0
	s_nop 1
	v_permlane32_swap_b32_e32 v168, v170
	v_permlane32_swap_b32_e32 v169, v171
	v_permlane32_swap_b32_e32 v0, v14
	s_branch .Lattn_h1_join
.Lh1_skip_g3:
	s_cmp_eq_u32 s98, 0
	s_cbranch_scc1 .Lsk1_ng3
	v_mfma_f32_32x32x16_bf16 v[32:47], v[18:21], v[236:239], v[32:47]
	v_mfma_f32_32x32x16_bf16 v[32:47], v[22:25], v[240:243], v[32:47]
	v_mfma_f32_32x32x16_bf16 v[32:47], v[26:29], v[246:249], v[32:47]
	v_mfma_f32_32x32x16_bf16 v[32:47], v[168:171], v[250:253], v[32:47]
.Lsk1_ng3:
	v_cmp_gt_f32_e32 vcc, 1.0, v235
	s_cbranch_vccz .Lsk1_norsc
	s_and_saveexec_b64 s[78:79], s[8:9]
	ds_write_b32 v192, v235 offset:128
	s_or_b64 exec, exec, s[78:79]
	s_waitcnt lgkmcnt(0)
	ds_read_b128 v[18:21], v189 offset:224
	ds_read_b128 v[22:25], v189 offset:192
	ds_read_b128 v[26:29], v189 offset:160
	ds_read_b128 v[168:171], v189 offset:128
	s_waitcnt lgkmcnt(3)
	v_pk_mul_f32 v[94:95], v[94:95], v[20:21]
	s_waitcnt lgkmcnt(2)
	v_pk_mul_f32 v[90:91], v[90:91], v[24:25]
	s_waitcnt lgkmcnt(1)
	v_pk_mul_f32 v[86:87], v[86:87], v[28:29]
	s_waitcnt lgkmcnt(0)
	v_pk_mul_f32 v[82:83], v[82:83], v[170:171]
	v_pk_mul_f32 v[92:93], v[92:93], v[18:19]
	v_pk_mul_f32 v[88:89], v[88:89], v[22:23]
	v_pk_mul_f32 v[84:85], v[84:85], v[26:27]
	v_pk_mul_f32 v[80:81], v[80:81], v[168:169]
	v_pk_mul_f32 v[78:79], v[78:79], v[20:21]
	v_pk_mul_f32 v[74:75], v[74:75], v[24:25]
	v_pk_mul_f32 v[70:71], v[70:71], v[28:29]
	v_pk_mul_f32 v[66:67], v[66:67], v[170:171]
	v_pk_mul_f32 v[76:77], v[76:77], v[18:19]
	v_pk_mul_f32 v[72:73], v[72:73], v[22:23]
	v_pk_mul_f32 v[68:69], v[68:69], v[26:27]
	v_pk_mul_f32 v[64:65], v[64:65], v[168:169]
	v_pk_mul_f32 v[62:63], v[62:63], v[20:21]
	v_pk_mul_f32 v[58:59], v[58:59], v[24:25]
	v_pk_mul_f32 v[54:55], v[54:55], v[28:29]
	v_pk_mul_f32 v[50:51], v[50:51], v[170:171]
	v_pk_mul_f32 v[60:61], v[60:61], v[18:19]
	v_pk_mul_f32 v[56:57], v[56:57], v[22:23]
	v_pk_mul_f32 v[52:53], v[52:53], v[26:27]
	v_pk_mul_f32 v[48:49], v[48:49], v[168:169]
	v_pk_mul_f32 v[46:47], v[46:47], v[20:21]
	v_pk_mul_f32 v[42:43], v[42:43], v[24:25]
	v_pk_mul_f32 v[38:39], v[38:39], v[28:29]
	v_pk_mul_f32 v[34:35], v[34:35], v[170:171]
	v_pk_mul_f32 v[44:45], v[44:45], v[18:19]
	v_pk_mul_f32 v[40:41], v[40:41], v[22:23]
	v_pk_mul_f32 v[36:37], v[36:37], v[26:27]
	v_pk_mul_f32 v[32:33], v[32:33], v[168:169]
.Lsk1_norsc:
	v_fmamk_f32 v168, v102, 0x3dd53b94, v254
	v_fmamk_f32 v169, v103, 0x3dd53b94, v254
	v_fmamk_f32 v170, v100, 0x3dd53b94, v254
	v_fmamk_f32 v171, v101, 0x3dd53b94, v254

.Lh1_nomask:
	s_mov_b32 s98, 0
	s_add_i32 s10, s54, 0xffffff81
	s_cmp_gt_i32 s10, s5
	s_cbranch_scc1 .Lh1_nopv
	s_mov_b32 s98, 1
	ds_read_b64_tr_b16 v[236:237], v190 offset:0
	ds_read_b64_tr_b16 v[238:239], v190 offset:2048
	ds_read_b64_tr_b16 v[240:241], v190 offset:4096
	ds_read_b64_tr_b16 v[242:243], v190 offset:6144
	ds_read_b64_tr_b16 v[246:247], v190 offset:8192
	ds_read_b64_tr_b16 v[248:249], v190 offset:10240
	ds_read_b64_tr_b16 v[250:251], v190 offset:12288
	ds_read_b64_tr_b16 v[252:253], v190 offset:14336
	v_max_f32_e32 v15, v113, v113
	v_max_f32_e32 v17, v112, v112
	v_max_f32_e32 v15, v17, v15
	v_max3_f32 v15, v15, v114, v115
	v_max3_f32 v15, v15, v116, v117
	v_max3_f32 v15, v15, v118, v119
	v_max3_f32 v15, v15, v120, v121
	v_max3_f32 v15, v15, v122, v123
	v_max3_f32 v15, v15, v124, v125
	v_max3_f32 v15, v15, v126, v127
	v_max3_f32 v15, v15, v96, v97
	v_max3_f32 v15, v15, v98, v99
	v_max3_f32 v15, v15, v100, v101
	v_max3_f32 v15, v15, v102, v103
	v_max3_f32 v15, v15, v104, v105
	v_max3_f32 v15, v15, v106, v107
	v_max3_f32 v15, v15, v108, v109
	v_max3_f32 v15, v15, v110, v111
	s_waitcnt lgkmcnt(6)
	v_mfma_f32_32x32x16_bf16 v[80:95], v[18:21], v[236:239], v[80:95]
	ds_read_b64_tr_b16 v[236:237], v190 offset:512
	ds_read_b64_tr_b16 v[238:239], v190 offset:2560
	v_mov_b32_e32 v17, v15
	s_nop 1
	v_permlane32_swap_b32_e32 v15, v17
	v_max_f32_e32 v17, v17, v17
	v_max_f32_e32 v15, v15, v15
	s_waitcnt lgkmcnt(6)
	v_mfma_f32_32x32x16_bf16 v[80:95], v[22:25], v[240:243], v[80:95]
	ds_read_b64_tr_b16 v[240:241], v190 offset:4608
	ds_read_b64_tr_b16 v[242:243], v190 offset:6656
	v_max_f32_e32 v15, v15, v17
	v_sub_f32_e32 v17, v15, v208
	v_mul_f32_e32 v17, 0x3d93cd3a, v17
	v_cmp_ge_f32_e32 vcc, s86, v17
	v_max_f32_e32 v17, v208, v208
	s_waitcnt lgkmcnt(6)
	v_mfma_f32_32x32x16_bf16 v[80:95], v[26:29], v[246:249], v[80:95]
	ds_read_b64_tr_b16 v[246:247], v190 offset:8704
	ds_read_b64_tr_b16 v[248:249], v190 offset:10752
	v_max_f32_e32 v17, v17, v15
	v_sub_f32_e32 v15, v208, v17
	v_mul_f32_e32 v15, 0x3dd53b94, v15
	v_exp_f32_e32 v15, v15
	s_cmp_eq_u64 vcc, exec
	s_waitcnt lgkmcnt(6)
	v_mfma_f32_32x32x16_bf16 v[80:95], v[168:171], v[250:253], v[80:95]
	ds_read_b64_tr_b16 v[250:251], v190 offset:12800
	ds_read_b64_tr_b16 v[252:253], v190 offset:14848
	s_cselect_b64 s[10:11], -1, 0
	v_cndmask_b32_e64 v180, v17, v208, s[10:11]
	v_cndmask_b32_e64 v15, v15, 1.0, s[10:11]
	v_mul_f32_e32 v219, 0xbdd53b94, v180
	v_fmamk_f32 v216, v112, 0x3dd53b94, v219
	s_waitcnt lgkmcnt(6)
	v_mfma_f32_32x32x16_bf16 v[64:79], v[18:21], v[236:239], v[64:79]
	ds_read_b64_tr_b16 v[236:237], v190 offset:1024
	ds_read_b64_tr_b16 v[238:239], v190 offset:3072
	v_fmamk_f32 v218, v113, 0x3dd53b94, v219
	v_fmamk_f32 v214, v114, 0x3dd53b94, v219
	v_fmamk_f32 v217, v115, 0x3dd53b94, v219
	v_fmamk_f32 v212, v116, 0x3dd53b94, v219
	v_fmamk_f32 v215, v117, 0x3dd53b94, v219
	s_waitcnt lgkmcnt(6)
	v_mfma_f32_32x32x16_bf16 v[64:79], v[22:25], v[240:243], v[64:79]
	ds_read_b64_tr_b16 v[240:241], v190 offset:5120
	ds_read_b64_tr_b16 v[242:243], v190 offset:7168
	v_fmamk_f32 v211, v118, 0x3dd53b94, v219
	v_fmamk_f32 v213, v119, 0x3dd53b94, v219
	v_fmamk_f32 v182, v120, 0x3dd53b94, v219
	v_fmamk_f32 v208, v121, 0x3dd53b94, v219
	v_fmamk_f32 v183, v123, 0x3dd53b94, v219
	s_waitcnt lgkmcnt(6)
	v_mfma_f32_32x32x16_bf16 v[64:79], v[26:29], v[246:249], v[64:79]
	ds_read_b64_tr_b16 v[246:247], v190 offset:9216
	ds_read_b64_tr_b16 v[248:249], v190 offset:11264
	v_fmamk_f32 v181, v125, 0x3dd53b94, v219
	v_exp_f32_e32 v216, v216
	v_fmamk_f32 v220, v96, 0x3dd53b94, v219
	v_exp_f32_e32 v218, v218
	s_waitcnt lgkmcnt(6)
	v_mfma_f32_32x32x16_bf16 v[64:79], v[168:171], v[250:253], v[64:79]
	ds_read_b64_tr_b16 v[250:251], v190 offset:13312
	ds_read_b64_tr_b16 v[252:253], v190 offset:15360
	v_fmamk_f32 v221, v97, 0x3dd53b94, v219
	v_exp_f32_e32 v214, v214
	v_fmamk_f32 v222, v98, 0x3dd53b94, v219
	v_exp_f32_e32 v217, v217
	s_waitcnt lgkmcnt(6)
	v_mfma_f32_32x32x16_bf16 v[48:63], v[18:21], v[236:239], v[48:63]
	ds_read_b64_tr_b16 v[236:237], v190 offset:1536
	ds_read_b64_tr_b16 v[238:239], v190 offset:3584
	v_fmamk_f32 v223, v99, 0x3dd53b94, v219
	v_exp_f32_e32 v212, v212
	v_fmamk_f32 v224, v100, 0x3dd53b94, v219
	v_exp_f32_e32 v215, v215
	s_waitcnt lgkmcnt(6)
	v_mfma_f32_32x32x16_bf16 v[48:63], v[22:25], v[240:243], v[48:63]
	ds_read_b64_tr_b16 v[240:241], v190 offset:5632
	ds_read_b64_tr_b16 v[242:243], v190 offset:7680
	v_fmamk_f32 v225, v101, 0x3dd53b94, v219
	v_exp_f32_e32 v211, v211
	v_fmamk_f32 v226, v102, 0x3dd53b94, v219
	v_exp_f32_e32 v213, v213
	s_waitcnt lgkmcnt(6)
	v_mfma_f32_32x32x16_bf16 v[48:63], v[26:29], v[246:249], v[48:63]
	ds_read_b64_tr_b16 v[246:247], v190 offset:9728
	ds_read_b64_tr_b16 v[248:249], v190 offset:11776
	v_fmamk_f32 v227, v103, 0x3dd53b94, v219
	v_fmamk_f32 v228, v104, 0x3dd53b94, v219
	v_fmamk_f32 v229, v105, 0x3dd53b94, v219
	v_fmamk_f32 v230, v106, 0x3dd53b94, v219
	s_waitcnt lgkmcnt(6)
	v_mfma_f32_32x32x16_bf16 v[48:63], v[168:171], v[250:253], v[48:63]
	ds_read_b64_tr_b16 v[250:251], v190 offset:13824
	ds_read_b64_tr_b16 v[252:253], v190 offset:15872
	v_fmamk_f32 v231, v107, 0x3dd53b94, v219
	v_fmamk_f32 v232, v108, 0x3dd53b94, v219
	v_fmamk_f32 v233, v109, 0x3dd53b94, v219
	v_fmamk_f32 v234, v110, 0x3dd53b94, v219
	s_branch .Lh1_kw

.Lh1_kw:
	s_waitcnt vmcnt(0)
	ds_write_b128 v202, v[6:9] offset:32768
	ds_write_b128 v202, v[160:163] offset:45056
	ds_write_b128 v203, v[164:167] offset:32768
	s_add_i32 s10, s54, 1
	s_waitcnt lgkmcnt(0)
	s_barrier
	ds_write_b128 v200, v[2:5]
	ds_write_b128 v201, v[10:13]
	s_cmp_gt_i32 s10, s5
	s_cbranch_scc1 .Lh2_skip_g3
	v_mfma_f32_32x32x16_bf16 v[32:47], v[18:21], v[236:239], v[32:47]
	ds_read_b128 v[236:239], v196 offset:32768
	v_mfma_f32_32x32x16_bf16 v[32:47], v[22:25], v[240:243], v[32:47]
	ds_read_b128 v[240:243], v196 offset:45056
	v_mfma_f32_32x32x16_bf16 v[32:47], v[26:29], v[246:249], v[32:47]
	ds_read_b128 v[246:249], v197 offset:32768
	v_mfma_f32_32x32x16_bf16 v[32:47], v[168:171], v[250:253], v[32:47]
	ds_read_b128 v[250:253], v197 offset:45056
	ds_read_b128 v[6:9], v195
	ds_read_b128 v[10:13], v195 offset:1024
	ds_read_b128 v[2:5], v195 offset:2048
	v_cmp_gt_f32_e32 vcc, 1.0, v15
	s_cbranch_vccz .Lqh2_norsc
	s_and_saveexec_b64 s[78:79], s[8:9]
	ds_write_b32 v192, v15 offset:128
	s_or_b64 exec, exec, s[78:79]
	s_waitcnt lgkmcnt(0)
	ds_read_b128 v[18:21], v189 offset:224
	ds_read_b128 v[22:25], v189 offset:192
	ds_read_b128 v[26:29], v189 offset:160
	ds_read_b128 v[168:171], v189 offset:128
	s_waitcnt lgkmcnt(3)
	v_pk_mul_f32 v[94:95], v[94:95], v[20:21]
	s_waitcnt lgkmcnt(2)
	v_pk_mul_f32 v[90:91], v[90:91], v[24:25]
	s_waitcnt lgkmcnt(1)
	v_pk_mul_f32 v[86:87], v[86:87], v[28:29]
	s_waitcnt lgkmcnt(0)
	v_pk_mul_f32 v[82:83], v[82:83], v[170:171]
	v_pk_mul_f32 v[92:93], v[92:93], v[18:19]
	v_pk_mul_f32 v[88:89], v[88:89], v[22:23]
	v_pk_mul_f32 v[84:85], v[84:85], v[26:27]
	v_pk_mul_f32 v[80:81], v[80:81], v[168:169]
	v_pk_mul_f32 v[78:79], v[78:79], v[20:21]
	v_pk_mul_f32 v[74:75], v[74:75], v[24:25]
	v_pk_mul_f32 v[70:71], v[70:71], v[28:29]
	v_pk_mul_f32 v[66:67], v[66:67], v[170:171]
	v_pk_mul_f32 v[76:77], v[76:77], v[18:19]
	v_pk_mul_f32 v[72:73], v[72:73], v[22:23]
	v_pk_mul_f32 v[68:69], v[68:69], v[26:27]
	v_pk_mul_f32 v[64:65], v[64:65], v[168:169]
	v_pk_mul_f32 v[62:63], v[62:63], v[20:21]
	v_pk_mul_f32 v[58:59], v[58:59], v[24:25]
	v_pk_mul_f32 v[54:55], v[54:55], v[28:29]
	v_pk_mul_f32 v[50:51], v[50:51], v[170:171]
	v_pk_mul_f32 v[60:61], v[60:61], v[18:19]
	v_pk_mul_f32 v[56:57], v[56:57], v[22:23]
	v_pk_mul_f32 v[52:53], v[52:53], v[26:27]
	v_pk_mul_f32 v[48:49], v[48:49], v[168:169]
	v_pk_mul_f32 v[46:47], v[46:47], v[20:21]
	v_pk_mul_f32 v[42:43], v[42:43], v[24:25]
	v_pk_mul_f32 v[38:39], v[38:39], v[28:29]
	v_pk_mul_f32 v[34:35], v[34:35], v[170:171]
	v_pk_mul_f32 v[44:45], v[44:45], v[18:19]
	v_pk_mul_f32 v[40:41], v[40:41], v[22:23]
	v_pk_mul_f32 v[36:37], v[36:37], v[26:27]
	v_pk_mul_f32 v[32:33], v[32:33], v[168:169]
.Lqh2_norsc:
	v_fmamk_f32 v171, v122, 0x3dd53b94, v219
	v_fmamk_f32 v169, v124, 0x3dd53b94, v219
	v_fmamk_f32 v168, v126, 0x3dd53b94, v219
	v_fmamk_f32 v170, v127, 0x3dd53b94, v219
	v_fmac_f32_e32 v219, 0x3dd53b94, v111
	v_exp_f32_e32 v182, v182
	v_exp_f32_e32 v208, v208
	v_exp_f32_e32 v171, v171
	v_exp_f32_e32 v183, v183
	v_exp_f32_e32 v169, v169
	v_exp_f32_e32 v181, v181
	v_exp_f32_e32 v168, v168
	v_exp_f32_e32 v170, v170
	v_cvt_pk_bf16_f32 v18, v216, v218
	v_cvt_pk_bf16_f32 v19, v214, v217
	v_cvt_pk_bf16_f32 v20, v212, v215
	v_cvt_pk_bf16_f32 v21, v211, v213
	v_cvt_pk_bf16_f32 v22, v182, v208
	v_cvt_pk_bf16_f32 v23, v171, v183
	v_cvt_pk_bf16_f32 v24, v169, v181
	v_cvt_pk_bf16_f32 v25, v168, v170
	v_add_f32_e32 v17, 0, v216
	v_add_f32_e32 v17, v218, v17
	v_add_f32_e32 v17, v214, v17
	v_add_f32_e32 v17, v217, v17
	v_add_f32_e32 v17, v212, v17
	v_add_f32_e32 v17, v215, v17
	v_add_f32_e32 v17, v211, v17
	v_add_f32_e32 v17, v213, v17
	s_waitcnt lgkmcnt(6)
	v_mfma_f32_32x32x16_bf16 v[112:127], v[236:239], v[156:159], 0
	ds_read_b128 v[236:239], v199 offset:32768
	v_add_f32_e32 v17, v182, v17
	v_add_f32_e32 v17, v208, v17
	v_permlane32_swap_b32_e32 v18, v20
	s_waitcnt lgkmcnt(6)
	v_mfma_f32_32x32x16_bf16 v[96:111], v[240:243], v[156:159], 0
	ds_read_b128 v[240:243], v199 offset:45056
	v_add_f32_e32 v17, v171, v17
	v_add_f32_e32 v17, v183, v17
	v_permlane32_swap_b32_e32 v19, v21
	s_waitcnt lgkmcnt(6)
	v_mfma_f32_32x32x16_bf16 v[112:127], v[246:249], v[152:155], v[112:127]
	ds_read_b128 v[246:249], v198 offset:32768
	v_add_f32_e32 v17, v169, v17
	v_add_f32_e32 v17, v181, v17
	s_waitcnt lgkmcnt(6)
	v_mfma_f32_32x32x16_bf16 v[96:111], v[250:253], v[152:155], v[96:111]
	ds_read_b128 v[250:253], v198 offset:45056
	v_permlane32_swap_b32_e32 v22, v24
	v_add_f32_e32 v17, v168, v17
	s_waitcnt lgkmcnt(3)
	v_mfma_f32_32x32x16_bf16 v[112:127], v[236:239], v[148:151], v[112:127]
	ds_read_b128 v[236:239], v196 offset:32896
	v_add_f32_e32 v17, v170, v17
	v_permlane32_swap_b32_e32 v23, v25
	s_waitcnt lgkmcnt(3)
	v_mfma_f32_32x32x16_bf16 v[96:111], v[240:243], v[148:151], v[96:111]
	ds_read_b128 v[240:243], v196 offset:45184
	v_exp_f32_e32 v220, v220
	v_exp_f32_e32 v221, v221
	s_waitcnt lgkmcnt(3)
	v_mfma_f32_32x32x16_bf16 v[112:127], v[246:249], v[144:147], v[112:127]
	ds_read_b128 v[246:249], v197 offset:32896
	v_exp_f32_e32 v222, v222
	v_exp_f32_e32 v223, v223
	s_waitcnt lgkmcnt(3)
	v_mfma_f32_32x32x16_bf16 v[96:111], v[250:253], v[144:147], v[96:111]
	ds_read_b128 v[250:253], v197 offset:45184
	v_add_f32_e32 v17, v220, v17
	v_exp_f32_e32 v224, v224
	s_waitcnt lgkmcnt(3)
	v_mfma_f32_32x32x16_bf16 v[112:127], v[236:239], v[140:143], v[112:127]
	ds_read_b128 v[236:239], v199 offset:32896
	v_add_f32_e32 v17, v221, v17
	v_exp_f32_e32 v225, v225
	s_waitcnt lgkmcnt(3)
	v_mfma_f32_32x32x16_bf16 v[96:111], v[240:243], v[140:143], v[96:111]
	ds_read_b128 v[240:243], v199 offset:45184
	v_add_f32_e32 v17, v222, v17
	v_exp_f32_e32 v226, v226
	s_waitcnt lgkmcnt(3)
	v_mfma_f32_32x32x16_bf16 v[112:127], v[246:249], v[136:139], v[112:127]
	ds_read_b128 v[246:249], v198 offset:32896
	v_add_f32_e32 v17, v223, v17
	v_exp_f32_e32 v227, v227
	s_waitcnt lgkmcnt(3)
	v_mfma_f32_32x32x16_bf16 v[96:111], v[250:253], v[136:139], v[96:111]
	ds_read_b128 v[250:253], v198 offset:45184
	v_cvt_pk_bf16_f32 v26, v220, v221
	v_cvt_pk_bf16_f32 v27, v222, v223
	s_waitcnt lgkmcnt(3)
	v_mfma_f32_32x32x16_bf16 v[112:127], v[236:239], v[132:135], v[112:127]
	ds_read_b128 v[236:239], v196 offset:33024
	v_add_f32_e32 v17, v224, v17
	v_exp_f32_e32 v228, v228
	s_waitcnt lgkmcnt(3)
	v_mfma_f32_32x32x16_bf16 v[96:111], v[240:243], v[132:135], v[96:111]
	ds_read_b128 v[240:243], v196 offset:45312
	v_add_f32_e32 v17, v225, v17
	v_exp_f32_e32 v229, v229
	s_waitcnt lgkmcnt(3)
	v_mfma_f32_32x32x16_bf16 v[112:127], v[246:249], v[128:131], v[112:127]
	ds_read_b128 v[246:249], v197 offset:33024
	v_add_f32_e32 v17, v226, v17
	v_exp_f32_e32 v230, v230
	s_waitcnt lgkmcnt(3)
	v_mfma_f32_32x32x16_bf16 v[96:111], v[250:253], v[128:131], v[96:111]
	ds_read_b128 v[250:253], v197 offset:45312
	v_add_f32_e32 v17, v227, v17
	v_exp_f32_e32 v231, v231
	s_waitcnt lgkmcnt(3)
	v_mfma_f32_32x32x16_bf16 v[112:127], v[236:239], v[6:9], v[112:127]
	ds_read_b128 v[236:239], v199 offset:33024
	v_cvt_pk_bf16_f32 v28, v224, v225
	v_cvt_pk_bf16_f32 v29, v226, v227
	s_waitcnt lgkmcnt(3)
	v_mfma_f32_32x32x16_bf16 v[96:111], v[240:243], v[6:9], v[96:111]
	ds_read_b128 v[240:243], v199 offset:45312
	ds_read_b128 v[6:9], v195 offset:3072
	v_add_f32_e32 v17, v228, v17
	v_exp_f32_e32 v232, v232
	s_waitcnt lgkmcnt(4)
	v_mfma_f32_32x32x16_bf16 v[112:127], v[246:249], v[10:13], v[112:127]
	ds_read_b128 v[246:249], v198 offset:33024
	v_permlane32_swap_b32_e32 v26, v28
	v_permlane32_swap_b32_e32 v27, v29
	s_waitcnt lgkmcnt(4)
	v_mfma_f32_32x32x16_bf16 v[96:111], v[250:253], v[10:13], v[96:111]
	ds_read_b128 v[250:253], v198 offset:45312
	v_add_f32_e32 v17, v229, v17
	v_exp_f32_e32 v233, v233
	s_waitcnt lgkmcnt(4)
	v_mfma_f32_32x32x16_bf16 v[112:127], v[236:239], v[2:5], v[112:127]
	v_add_f32_e32 v17, v230, v17
	v_exp_f32_e32 v234, v234
	s_waitcnt lgkmcnt(3)
	v_mfma_f32_32x32x16_bf16 v[96:111], v[240:243], v[2:5], v[96:111]
	v_add_f32_e32 v17, v231, v17
	v_exp_f32_e32 v219, v219
	s_waitcnt lgkmcnt(1)
	v_mfma_f32_32x32x16_bf16 v[112:127], v[246:249], v[6:9], v[112:127]
	v_cvt_pk_bf16_f32 v168, v228, v229
	v_cvt_pk_bf16_f32 v169, v230, v231
	s_waitcnt lgkmcnt(0)
	v_mfma_f32_32x32x16_bf16 v[96:111], v[250:253], v[6:9], v[96:111]
	v_add_f32_e32 v17, v232, v17
	v_add_f32_e32 v17, v233, v17
	v_add_f32_e32 v17, v234, v17
	v_add_f32_e32 v17, v219, v17
	v_cvt_pk_bf16_f32 v170, v232, v233
	v_cvt_pk_bf16_f32 v171, v234, v219
	v_mov_b32_e32 v30, v17
	s_nop 1
	v_permlane32_swap_b32_e32 v168, v170
	v_permlane32_swap_b32_e32 v169, v171
	v_permlane32_swap_b32_e32 v17, v30
	s_branch .Lattn_h2_join

.Lsk2_norsc:
	v_fmamk_f32 v171, v122, 0x3dd53b94, v219
	v_fmamk_f32 v169, v124, 0x3dd53b94, v219
	v_fmamk_f32 v168, v126, 0x3dd53b94, v219
	v_fmamk_f32 v170, v127, 0x3dd53b94, v219
	v_fmac_f32_e32 v219, 0x3dd53b94, v111
.LBB0_407:
	v_exp_f32_e32 v182, v182
	v_exp_f32_e32 v208, v208
	v_exp_f32_e32 v171, v171
	v_exp_f32_e32 v183, v183
	v_exp_f32_e32 v169, v169
	v_exp_f32_e32 v181, v181
	v_exp_f32_e32 v168, v168
	v_exp_f32_e32 v170, v170
	v_mov_b32_e32 v30, v16
	v_mov_b32_e32 v31, v16
	v_mov_b32_e32 v17, v16
	v_mov_b32_e32 v18, v16
	v_mov_b32_e32 v19, v16
	v_mov_b32_e32 v20, v16
	v_mov_b32_e32 v21, v16
	v_mov_b32_e32 v22, v16
	v_mov_b32_e32 v23, v16
	v_mov_b32_e32 v24, v16
	v_mov_b32_e32 v25, v16
	v_mov_b32_e32 v26, v16
	v_mov_b32_e32 v27, v16
	v_mov_b32_e32 v28, v16
	v_mov_b32_e32 v29, v16
	v_mov_b64_e32 v[126:127], v[30:31]
	v_mov_b64_e32 v[110:111], v[30:31]
	v_mov_b64_e32 v[124:125], v[28:29]
	v_mov_b64_e32 v[122:123], v[26:27]
	v_mov_b64_e32 v[120:121], v[24:25]
	v_mov_b64_e32 v[118:119], v[22:23]
	v_mov_b64_e32 v[116:117], v[20:21]
	v_mov_b64_e32 v[114:115], v[18:19]
	v_mov_b64_e32 v[112:113], v[16:17]
	v_mov_b64_e32 v[108:109], v[28:29]
	v_mov_b64_e32 v[106:107], v[26:27]
	v_mov_b64_e32 v[104:105], v[24:25]
	v_mov_b64_e32 v[102:103], v[22:23]
	v_mov_b64_e32 v[100:101], v[20:21]
	v_mov_b64_e32 v[98:99], v[18:19]
	v_mov_b64_e32 v[96:97], v[16:17]

.Lh2_nomask:
	s_mov_b32 s98, 0
	s_andn2_b64 vcc, exec, s[76:77]
	s_cbranch_vccnz .Lh2_nopv
	s_mov_b32 s98, 1
	ds_read_b64_tr_b16 v[236:237], v190 offset:16384
	ds_read_b64_tr_b16 v[238:239], v190 offset:18432
	ds_read_b64_tr_b16 v[240:241], v190 offset:20480
	ds_read_b64_tr_b16 v[242:243], v190 offset:22528
	ds_read_b64_tr_b16 v[246:247], v190 offset:24576
	ds_read_b64_tr_b16 v[248:249], v190 offset:26624
	ds_read_b64_tr_b16 v[250:251], v190 offset:28672
	ds_read_b64_tr_b16 v[252:253], v190 offset:30720
	v_max_f32_e32 v255, v113, v113
	v_max_f32_e32 v245, v112, v112
	v_max_f32_e32 v255, v245, v255
	v_max3_f32 v255, v255, v114, v115
	v_max3_f32 v255, v255, v116, v117
	v_max3_f32 v255, v255, v118, v119
	v_max3_f32 v255, v255, v120, v121
	v_max3_f32 v255, v255, v122, v123
	v_max3_f32 v255, v255, v124, v125
	v_max3_f32 v255, v255, v126, v127
	v_max3_f32 v255, v255, v96, v97
	v_max3_f32 v255, v255, v98, v99
	v_max3_f32 v255, v255, v100, v101
	v_max3_f32 v255, v255, v102, v103
	v_max3_f32 v255, v255, v104, v105
	v_max3_f32 v255, v255, v106, v107
	v_max3_f32 v255, v255, v108, v109
	v_max3_f32 v255, v255, v110, v111
	s_waitcnt lgkmcnt(6)
	v_mfma_f32_32x32x16_bf16 v[80:95], v[18:21], v[236:239], v[80:95]
	ds_read_b64_tr_b16 v[236:237], v190 offset:16896
	ds_read_b64_tr_b16 v[238:239], v190 offset:18944
	v_mov_b32_e32 v245, v255
	s_nop 1
	v_permlane32_swap_b32_e32 v255, v245
	v_max_f32_e32 v245, v245, v245
	v_max_f32_e32 v255, v255, v255
	s_waitcnt lgkmcnt(6)
	v_mfma_f32_32x32x16_bf16 v[80:95], v[22:25], v[240:243], v[80:95]
	ds_read_b64_tr_b16 v[240:241], v190 offset:20992
	ds_read_b64_tr_b16 v[242:243], v190 offset:23040
	v_max_f32_e32 v255, v255, v245
	v_sub_f32_e32 v245, v255, v180
	v_mul_f32_e32 v245, 0x3d93cd3a, v245
	v_cmp_ge_f32_e32 vcc, s86, v245
	s_cmp_eq_u64 vcc, exec
	s_waitcnt lgkmcnt(6)
	v_mfma_f32_32x32x16_bf16 v[80:95], v[26:29], v[246:249], v[80:95]
	ds_read_b64_tr_b16 v[246:247], v190 offset:25088
	ds_read_b64_tr_b16 v[248:249], v190 offset:27136
	s_cselect_b64 s[10:11], -1, 0
	v_max_f32_e32 v235, v180, v180
	v_max_f32_e32 v245, v235, v255
	v_sub_f32_e32 v235, v180, v245
	v_mul_f32_e32 v235, 0x3dd53b94, v235
	s_waitcnt lgkmcnt(6)
	v_mfma_f32_32x32x16_bf16 v[80:95], v[168:171], v[250:253], v[80:95]
	ds_read_b64_tr_b16 v[250:251], v190 offset:29184
	ds_read_b64_tr_b16 v[252:253], v190 offset:31232
	v_exp_f32_e32 v235, v235
	v_cndmask_b32_e64 v208, v245, v180, s[10:11]
	v_cndmask_b32_e64 v235, v235, 1.0, s[10:11]
	v_mul_f32_e32 v254, 0xbdd53b94, v208
	v_mov_b32_e32 v213, v254
	s_waitcnt lgkmcnt(6)
	v_mfma_f32_32x32x16_bf16 v[64:79], v[18:21], v[236:239], v[64:79]
	ds_read_b64_tr_b16 v[236:237], v190 offset:17408
	ds_read_b64_tr_b16 v[238:239], v190 offset:19456
	v_fmamk_f32 v224, v112, 0x3dd53b94, v254
	v_fmamk_f32 v226, v113, 0x3dd53b94, v254
	v_fmamk_f32 v222, v114, 0x3dd53b94, v254
	v_fmamk_f32 v225, v115, 0x3dd53b94, v254
	v_fmamk_f32 v220, v116, 0x3dd53b94, v254
	s_waitcnt lgkmcnt(6)
	v_mfma_f32_32x32x16_bf16 v[64:79], v[22:25], v[240:243], v[64:79]
	ds_read_b64_tr_b16 v[240:241], v190 offset:21504
	ds_read_b64_tr_b16 v[242:243], v190 offset:23552
	v_fmamk_f32 v223, v117, 0x3dd53b94, v254
	v_fmamk_f32 v219, v118, 0x3dd53b94, v254
	v_fmamk_f32 v221, v119, 0x3dd53b94, v254
	v_fmamk_f32 v216, v120, 0x3dd53b94, v254
	v_fmamk_f32 v218, v121, 0x3dd53b94, v254
	s_waitcnt lgkmcnt(6)
	v_mfma_f32_32x32x16_bf16 v[64:79], v[26:29], v[246:249], v[64:79]
	ds_read_b64_tr_b16 v[246:247], v190 offset:25600
	ds_read_b64_tr_b16 v[248:249], v190 offset:27648
	v_fmamk_f32 v214, v122, 0x3dd53b94, v254
	v_fmamk_f32 v217, v123, 0x3dd53b94, v254
	v_fmamk_f32 v212, v124, 0x3dd53b94, v254
	v_fmamk_f32 v215, v125, 0x3dd53b94, v254
	v_fmamk_f32 v211, v126, 0x3dd53b94, v254
	s_waitcnt lgkmcnt(6)
	v_mfma_f32_32x32x16_bf16 v[64:79], v[168:171], v[250:253], v[64:79]
	ds_read_b64_tr_b16 v[250:251], v190 offset:29696
	ds_read_b64_tr_b16 v[252:253], v190 offset:31744
	v_fmac_f32_e32 v213, 0x3dd53b94, v127
	v_exp_f32_e32 v224, v224
	v_exp_f32_e32 v226, v226
	v_exp_f32_e32 v222, v222
	v_exp_f32_e32 v225, v225
	s_waitcnt lgkmcnt(6)
	v_mfma_f32_32x32x16_bf16 v[48:63], v[18:21], v[236:239], v[48:63]
	ds_read_b64_tr_b16 v[236:237], v190 offset:17920
	ds_read_b64_tr_b16 v[238:239], v190 offset:19968
	v_exp_f32_e32 v220, v220
	v_exp_f32_e32 v223, v223
	v_exp_f32_e32 v219, v219
	v_exp_f32_e32 v221, v221
	s_waitcnt lgkmcnt(6)
	v_mfma_f32_32x32x16_bf16 v[48:63], v[22:25], v[240:243], v[48:63]
	ds_read_b64_tr_b16 v[240:241], v190 offset:22016
	ds_read_b64_tr_b16 v[242:243], v190 offset:24064
	v_exp_f32_e32 v216, v216
	v_exp_f32_e32 v218, v218
	v_exp_f32_e32 v214, v214
	v_exp_f32_e32 v217, v217
	s_waitcnt lgkmcnt(6)
	v_mfma_f32_32x32x16_bf16 v[48:63], v[26:29], v[246:249], v[48:63]
	ds_read_b64_tr_b16 v[246:247], v190 offset:26112
	ds_read_b64_tr_b16 v[248:249], v190 offset:28160
	v_exp_f32_e32 v212, v212
	v_exp_f32_e32 v215, v215
	v_exp_f32_e32 v211, v211
	v_exp_f32_e32 v213, v213
	s_waitcnt lgkmcnt(6)
	v_mfma_f32_32x32x16_bf16 v[48:63], v[168:171], v[250:253], v[48:63]
	ds_read_b64_tr_b16 v[250:251], v190 offset:30208
	ds_read_b64_tr_b16 v[252:253], v190 offset:32256
	v_fmamk_f32 v182, v96, 0x3dd53b94, v254
	v_fmamk_f32 v183, v97, 0x3dd53b94, v254
	v_fmamk_f32 v180, v98, 0x3dd53b94, v254
	v_fmamk_f32 v181, v99, 0x3dd53b94, v254
	s_branch .Lh2_kw
.Lh2_nopv:
	v_max_f32_e32 v255, v113, v113
	v_max_f32_e32 v245, v112, v112
	v_max_f32_e32 v255, v245, v255
	v_max3_f32 v255, v255, v114, v115
	v_max3_f32 v255, v255, v116, v117
	v_max3_f32 v255, v255, v118, v119
	v_max3_f32 v255, v255, v120, v121
	v_max3_f32 v255, v255, v122, v123
	v_max3_f32 v255, v255, v124, v125
	v_max3_f32 v255, v255, v126, v127
	v_max3_f32 v255, v255, v96, v97
	v_max3_f32 v255, v255, v98, v99
	v_max3_f32 v255, v255, v100, v101
	v_max3_f32 v255, v255, v102, v103
	v_max3_f32 v255, v255, v104, v105
	v_max3_f32 v255, v255, v106, v107
	v_max3_f32 v255, v255, v108, v109
	v_max3_f32 v255, v255, v110, v111
	v_mov_b32_e32 v245, v255
	s_nop 1
	v_permlane32_swap_b32_e32 v255, v245
	v_max_f32_e32 v245, v245, v245
	v_max_f32_e32 v255, v255, v255
	v_max_f32_e32 v255, v255, v245
	v_sub_f32_e32 v245, v255, v180
	v_mul_f32_e32 v245, 0x3d93cd3a, v245
	v_cmp_ge_f32_e32 vcc, s86, v245
	s_cmp_eq_u64 vcc, exec
	s_cselect_b64 s[10:11], -1, 0
	v_max_f32_e32 v235, v180, v180
	v_max_f32_e32 v245, v235, v255
	v_sub_f32_e32 v235, v180, v245
	v_mul_f32_e32 v235, 0x3dd53b94, v235
	v_exp_f32_e32 v235, v235
	v_cndmask_b32_e64 v208, v245, v180, s[10:11]
	v_cndmask_b32_e64 v235, v235, 1.0, s[10:11]
	v_mul_f32_e32 v254, 0xbdd53b94, v208
	v_mov_b32_e32 v213, v254
	v_fmamk_f32 v224, v112, 0x3dd53b94, v254
	v_fmamk_f32 v226, v113, 0x3dd53b94, v254
	v_fmamk_f32 v222, v114, 0x3dd53b94, v254
	v_fmamk_f32 v225, v115, 0x3dd53b94, v254
	v_fmamk_f32 v220, v116, 0x3dd53b94, v254
	v_fmamk_f32 v223, v117, 0x3dd53b94, v254
	v_fmamk_f32 v219, v118, 0x3dd53b94, v254
	v_fmamk_f32 v221, v119, 0x3dd53b94, v254
	v_fmamk_f32 v216, v120, 0x3dd53b94, v254
	v_fmamk_f32 v218, v121, 0x3dd53b94, v254
	v_fmamk_f32 v214, v122, 0x3dd53b94, v254
	v_fmamk_f32 v217, v123, 0x3dd53b94, v254
	v_fmamk_f32 v212, v124, 0x3dd53b94, v254
	v_fmamk_f32 v215, v125, 0x3dd53b94, v254
	v_fmamk_f32 v211, v126, 0x3dd53b94, v254
	v_fmac_f32_e32 v213, 0x3dd53b94, v127
	v_exp_f32_e32 v224, v224
	v_exp_f32_e32 v226, v226
	v_exp_f32_e32 v222, v222
	v_exp_f32_e32 v225, v225
	v_exp_f32_e32 v220, v220
	v_exp_f32_e32 v223, v223
	v_exp_f32_e32 v219, v219
	v_exp_f32_e32 v221, v221
	v_exp_f32_e32 v216, v216
	v_exp_f32_e32 v218, v218
	v_exp_f32_e32 v214, v214
	v_exp_f32_e32 v217, v217
	v_exp_f32_e32 v212, v212
	v_exp_f32_e32 v215, v215
	v_exp_f32_e32 v211, v211
	v_exp_f32_e32 v213, v213
	v_fmamk_f32 v182, v96, 0x3dd53b94, v254
	v_fmamk_f32 v183, v97, 0x3dd53b94, v254
	v_fmamk_f32 v180, v98, 0x3dd53b94, v254
	v_fmamk_f32 v181, v99, 0x3dd53b94, v254

.Lh2_post:
	v_fmamk_f32 v160, v110, 0x3dd53b94, v254
	v_fmamk_f32 v161, v111, 0x3dd53b94, v254
	v_fmamk_f32 v162, v108, 0x3dd53b94, v254
	v_fmamk_f32 v163, v109, 0x3dd53b94, v254
	v_fmamk_f32 v164, v106, 0x3dd53b94, v254
	v_fmamk_f32 v165, v107, 0x3dd53b94, v254
	v_fmamk_f32 v166, v104, 0x3dd53b94, v254
	v_fmamk_f32 v167, v105, 0x3dd53b94, v254
	v_add_f32_e32 v0, v0, v14
	s_mov_b64 s[10:11], 0x4000
	v_fmac_f32_e32 v0, v191, v194
	v_add_f32_e32 v194, v17, v30
	v_lshl_add_u64 v[176:177], v[176:177], 0, s[10:11]
	s_mov_b64 s[10:11], 0x200000
	s_addk_i32 s54, 0x80
	v_fmac_f32_e32 v194, v0, v15
	v_lshl_add_u64 v[178:179], v[178:179], 0, s[10:11]
	v_add_u32_e32 v210, 0xffffff80, v210
	v_mov_b32_e32 v191, v235
	s_waitcnt lgkmcnt(0)
	s_barrier
	s_andn2_b64 vcc, exec, s[78:79]
	s_cbranch_vccnz .Lh2_nov
	ds_write_b128 v200, v[2:5] offset:16384
	ds_write_b128 v201, v[10:13] offset:16384

.Lexit_norsc:
	v_fmamk_f32 v168, v102, 0x3dd53b94, v254
	v_fmamk_f32 v169, v103, 0x3dd53b94, v254
	v_fmamk_f32 v170, v100, 0x3dd53b94, v254
	v_fmamk_f32 v171, v101, 0x3dd53b94, v254
	s_branch .LBB0_420

	.amdhsa_kernel _Z13mla_hgrn2_fwd6Params
		.amdhsa_group_segment_fixed_size 0
		.amdhsa_private_segment_fixed_size 0
		.amdhsa_kernarg_size 520
		.amdhsa_user_sgpr_count 2
		.amdhsa_user_sgpr_dispatch_ptr 0
		.amdhsa_user_sgpr_queue_ptr 0
		.amdhsa_user_sgpr_kernarg_segment_ptr 1
		.amdhsa_user_sgpr_dispatch_id 0
		.amdhsa_user_sgpr_kernarg_preload_length 0
		.amdhsa_user_sgpr_kernarg_preload_offset 0
		.amdhsa_user_sgpr_private_segment_size 0
		.amdhsa_uses_dynamic_stack 0
		.amdhsa_enable_private_segment 0
		.amdhsa_system_sgpr_workgroup_id_x 1
		.amdhsa_system_sgpr_workgroup_id_y 0
		.amdhsa_system_sgpr_workgroup_id_z 0
		.amdhsa_system_sgpr_workgroup_info 0
		.amdhsa_system_vgpr_workitem_id 2
		.amdhsa_next_free_vgpr 256
		.amdhsa_next_free_sgpr 100
		.amdhsa_accum_offset 256
		.amdhsa_reserve_vcc 1
		.amdhsa_float_round_mode_32 0
		.amdhsa_float_round_mode_16_64 0
		.amdhsa_float_denorm_mode_32 3
		.amdhsa_float_denorm_mode_16_64 3
		.amdhsa_dx10_clamp 1
		.amdhsa_ieee_mode 1
		.amdhsa_fp16_overflow 0
		.amdhsa_tg_split 0
		.amdhsa_exception_fp_ieee_invalid_op 0
		.amdhsa_exception_fp_denorm_src 0
		.amdhsa_exception_fp_ieee_div_zero 0
		.amdhsa_exception_fp_ieee_overflow 0
		.amdhsa_exception_fp_ieee_underflow 0
		.amdhsa_exception_fp_ieee_inexact 0
		.amdhsa_exception_int_div_zero 0
	.end_amdhsa_kernel

amdhsa.kernels:
  - .agpr_count:     0
    .args:
      - .offset:         0
        .size:           264
        .value_kind:     by_value
      - .offset:         264
        .size:           4
        .value_kind:     hidden_block_count_x
      - .offset:         268
        .size:           4
        .value_kind:     hidden_block_count_y
      - .offset:         272
        .size:           4
        .value_kind:     hidden_block_count_z
      - .offset:         276
        .size:           2
        .value_kind:     hidden_group_size_x
      - .offset:         278
        .size:           2
        .value_kind:     hidden_group_size_y
      - .offset:         280
        .size:           2
        .value_kind:     hidden_group_size_z
      - .offset:         282
        .size:           2
        .value_kind:     hidden_remainder_x
      - .offset:         284
        .size:           2
        .value_kind:     hidden_remainder_y
      - .offset:         286
        .size:           2
        .value_kind:     hidden_remainder_z
      - .offset:         304
        .size:           8
        .value_kind:     hidden_global_offset_x
      - .offset:         312
        .size:           8
        .value_kind:     hidden_global_offset_y
      - .offset:         320
        .size:           8
        .value_kind:     hidden_global_offset_z
      - .offset:         328
        .size:           2
        .value_kind:     hidden_grid_dims
      - .offset:         352
        .size:           8
        .value_kind:     hidden_multigrid_sync_arg
      - .offset:         384
        .size:           4
        .value_kind:     hidden_dynamic_lds_size
    .group_segment_fixed_size: 0
    .kernarg_segment_align: 8
    .kernarg_segment_size: 520
    .language:       OpenCL C
    .language_version:
      - 2
      - 0
    .max_flat_workgroup_size: 512
    .name:           _Z13mla_hgrn2_fwd6Params
    .private_segment_fixed_size: 0
    .sgpr_count:     106
    .sgpr_spill_count: 10
    .symbol:         _Z13mla_hgrn2_fwd6Params.kd
    .uniform_work_group_size: 1
    .uses_dynamic_stack: false
    .vgpr_count:     256
    .vgpr_spill_count: 0
    .wavefront_size: 64
